# SB items: output-gate loads issued at item start instead of in the epilogue
# speedup vs baseline: 1.0082x; 1.0041x over previous
; #define LAS __attribute__((address_space(3)))
; __device__ __forceinline__ int next_item(unsigned* ctr, LAS unsigned* slot) {
;     __syncthreads();
;     if (threadIdx.x == 0) *slot = atomicAdd(ctr, 1u);
;     __syncthreads();
;     return (int)*slot;
; }
; __global__ void __launch_bounds__(512) hymba_fwd(Args a) {
;     ...
;                 for (;;) {
;                     const int idx = next_item(ctl + pb + 3 + 16 * rep, qslot);
;                     if (idx >= 1536) break;
;                     if (idx < 512) { const int qb = 15 - (idx >> 5), bh = idx & 31;
;     ...
;  attn_item<0>(ap, bh >> 2, bh & 3, qb, lds);
;     ...
;  }
;                     else { const int i2 = idx - 512, qb = 15 - (i2 >> 6), bh = i2 & 63;
.LBB0_472:
	s_or_b64 exec, exec, s[0:1]
	v_readlane_b32 s0, v254, 19
	s_waitcnt lgkmcnt(0)
	s_barrier
	v_mov_b32_e32 v0, s0
	ds_read_b32 v0, v0
	s_mov_b64 s[0:1], -1
	s_waitcnt lgkmcnt(0)
	v_cmp_lt_i32_e32 vcc, s75, v0
	v_readfirstlane_b32 s57, v0
	s_cbranch_vccnz .LBB0_469
	s_cmpk_gt_i32 s57, 0x1ff
	s_cbranch_scc0 .LBB0_491
; #define LAS __attribute__((address_space(3)))
; __device__ __forceinline__ unsigned pk2(float lo, float hi) { f32x2 v = {lo, hi}; bf16x2_t b = __builtin_convertvector(v, bf16x2_t); return __builtin_bit_cast(unsigned, b); }
; template <int MODE>
; __device__ __forceinline__ void attn_item(const AttnP& p, int b, int h, int qb, LAS unsigned char* lds) {
;     ...
;     const int qcol = ((MODE == 1) ? 2048 : 0) + h * DK, kcol = qcol + 512, vcol = qcol + 1024, gcol = qcol + 1536;
;     const int mixcol = ((MODE == 1) ? 512 : 0) + h * DV;
;     const int gaincol = ((MODE == 0) ? 0 : (MODE == 1) ? 512 : 1024) + h * DV;
;     const int tok0 = b * SEQ, q0 = qb * 256, qw = q0 + 32 * w, qrow = qw + ln;
;     const bf16_t* P = p.P;
;     bf16x8 Qf[NC][4];
; #pragma unroll
;     for (int c = 0; c < NC; ++c) {
;         u32x4 raw[4]; float ss = 0.f;
; #pragma unroll
;         for (int ks = 0; ks < 4; ++ks) {
;             raw[ks] = *(const u32x4*)(P + (size_t)(tok0 + qrow) * PP + qcol + c * 64 + ks * 16 + hh * 8);
; #pragma unroll
;             for (int e = 0; e < 4; ++e) { const float lo = bflo(raw[ks][e]), hi = bfhi(raw[ks][e]); ss += lo * lo + hi * hi; }
;         }
;         float sc = 0.125f * LOG2E;
;         if (MODE != 1) { ss += __shfl_xor(ss, 32); sc *= 1.0f / sqrtf(ss * (1.0f / 64.0f) + 1e-6f); }
; #pragma unroll
;         for (int ks = 0; ks < 4; ++ks) {
;             u32x4 o;
; #pragma unroll
;             for (int e = 0; e < 4; ++e) {
;                 float lo = bflo(raw[ks][e]) * sc, hi = bfhi(raw[ks][e]) * sc;
;                 if (MODE != 1) {
;                     const int d = ks * 16 + hh * 8 + 2 * e;
;                     const float* gq = p.qk_gain + ((MODE == 0) ? 0 : 128); const float* gk = gq + 64;
;                     lo *= gq[d] * gk[d]; hi *= gq[d + 1] * gk[d + 1];
;                 }
;                 o[e] = pk2(lo, hi);
;             }
;             Qf[c][ks] = __builtin_bit_cast(bf16x8, o);
;             if (QPARK) *(LAS u32x4*)(lds + QP_OFF + w * 8192 + ((c * 4 + ks) * 64 + lane) * 16) = o;
;         }
;     }
;     if (MODE == 0) { LAS float* tab = (LAS float*)(lds + TAB_OFF); if (tid < 256) tab[tid] = p.biasT[h * 256 + tid]; }
;     LAS unsigned* flags = (LAS unsigned*)(lds + FLAG_OFF);
;     if (MODE == 1 && tid < 16) flags[tid] = 0u;
;     ...
;     ATT_LOAD(jt_max);
;     ATT_STORE(0, jt_max);
;     __syncthreads();
	s_add_i32 s0, s57, 0xfffffe00
	v_mov_b32_e32 v18, v210
	s_lshr_b32 s2, s0, 6
	s_sub_i32 s4, 15, s2
	v_readfirstlane_b32 s0, v18
	s_ashr_i32 s3, s0, 6
	s_lshl_b32 s0, s57, 6
	s_and_b32 s20, s0, 0x1c0
	s_lshl_b32 s0, s57, 9
	s_and_b32 s33, s0, 0x7000
	s_lshl_b32 s0, s4, 8
	s_lshl_b32 s58, s3, 5
	v_and_b32_e32 v19, 31, v18
	s_add_i32 s58, s58, s0
	v_or_b32_e32 v86, s58, v19
	v_add_u32_e32 v0, s33, v86
	v_mov_b64_e32 v[2:3], s[46:47]
	v_bfe_u32 v20, v18, 5, 1
	v_mad_i64_i32 v[2:3], s[0:1], v0, s76, v[2:3]
	s_lshl_b32 s92, s20, 1
	v_lshl_add_u64 v[2:3], v[2:3], 0, s[92:93]
	v_lshlrev_b32_e32 v164, 3, v20
	v_mov_b32_e32 v165, 0
	v_lshl_add_u64 v[164:165], v[2:3], 0, v[164:165]
	v_add_co_u32_e32 v164, vcc, 0x1c00, v164
	s_nop 1
	v_addc_co_u32_e32 v165, vcc, 0, v165, vcc
	global_load_dwordx2 v[166:167], v[164:165], off offset:0
	global_load_dwordx2 v[168:169], v[164:165], off offset:16
	global_load_dwordx2 v[170:171], v[164:165], off offset:32
	global_load_dwordx2 v[172:173], v[164:165], off offset:48
	global_load_dwordx2 v[174:175], v[164:165], off offset:64
	global_load_dwordx2 v[176:177], v[164:165], off offset:80
	global_load_dwordx2 v[178:179], v[164:165], off offset:96
	global_load_dwordx2 v[180:181], v[164:165], off offset:112
	v_lshlrev_b32_e32 v0, 4, v20
	v_lshl_add_u64 v[2:3], v[2:3], 0, v[0:1]
	s_mov_b64 s[0:1], 0x1000
	v_lshl_add_u64 v[4:5], v[2:3], 0, s[0:1]
	v_add_co_u32_e32 v2, vcc, 0x1000, v2
	s_nop 1
	v_addc_co_u32_e32 v3, vcc, 0, v3, vcc
	global_load_dwordx4 v[10:13], v[4:5], off offset:32
	global_load_dwordx4 v[6:9], v[4:5], off offset:64
	global_load_dwordx4 v[14:17], v[2:3], off
	s_nop 0
	global_load_dwordx4 v[2:5], v[4:5], off offset:96
	v_cmp_gt_i32_e32 vcc, 16, v18
	s_and_saveexec_b64 s[0:1], vcc
	v_lshl_add_u32 v21, v18, 2, 0
	ds_write_b32 v21, v1 offset:44544
	s_or_b64 exec, exec, s[0:1]
	s_lshl_b32 s0, s4, 2
	s_or_b32 s59, s0, 3
	s_lshl_b32 s0, s59, 6
	v_ashrrev_i32_e32 v21, 3, v18
	s_or_b32 s0, s0, s33
	v_add_u32_e32 v24, s0, v21
	v_mov_b64_e32 v[22:23], s[46:47]
	v_mad_i64_i32 v[22:23], s[0:1], v24, s76, v[22:23]
	v_lshlrev_b32_e32 v24, 3, v18
	v_and_b32_e32 v24, 56, v24
	v_lshlrev_b32_e32 v26, 1, v24
	v_mov_b32_e32 v27, v1
	v_lshl_add_u64 v[22:23], v[22:23], 0, v[26:27]
	s_or_b32 s0, s92, 0x1400
	s_mov_b32 s1, s93
	v_lshl_add_u64 v[28:29], v[22:23], 0, s[0:1]
	s_or_b32 s4, s92, 0x1800
	s_mov_b32 s5, s93
	v_lshl_add_u64 v[22:23], v[22:23], 0, s[4:5]
	global_load_dwordx4 v[50:53], v[28:29], off
	global_load_dwordx4 v[58:61], v[22:23], off
	s_waitcnt vmcnt(0) lgkmcnt(0)
	v_lshlrev_b32_e32 v22, 16, v14
	v_and_b32_e32 v23, 0xffff0000, v14
	s_mov_b32 s6, 0x3e38aa3b
	v_lshlrev_b32_e32 v14, 16, v15
	v_and_b32_e32 v15, 0xffff0000, v15
	v_pk_mul_f32 v[14:15], v[14:15], s[6:7] op_sel_hi:[1,0]
	v_and_b32_e32 v25, 63, v18
	v_cvt_pk_bf16_f32 v55, v14, v15
	v_lshlrev_b32_e32 v14, 16, v16
	v_and_b32_e32 v15, 0xffff0000, v16
	v_pk_mul_f32 v[14:15], v[14:15], s[6:7] op_sel_hi:[1,0]
	v_pk_mul_f32 v[22:23], v[22:23], s[6:7] op_sel_hi:[1,0]
	v_cvt_pk_bf16_f32 v56, v14, v15
	v_lshlrev_b32_e32 v14, 16, v17
	v_and_b32_e32 v15, 0xffff0000, v17
	v_pk_mul_f32 v[14:15], v[14:15], s[6:7] op_sel_hi:[1,0]
	v_lshlrev_b32_e32 v87, 2, v20
	v_cvt_pk_bf16_f32 v57, v14, v15
	v_lshlrev_b32_e32 v14, 16, v10
	v_and_b32_e32 v15, 0xffff0000, v10
	v_lshlrev_b32_e32 v10, 16, v11
	v_and_b32_e32 v11, 0xffff0000, v11
	v_pk_mul_f32 v[10:11], v[10:11], s[6:7] op_sel_hi:[1,0]
	v_pk_mul_f32 v[14:15], v[14:15], s[6:7] op_sel_hi:[1,0]
	v_cvt_pk_bf16_f32 v63, v10, v11
	v_lshlrev_b32_e32 v10, 16, v12
	v_and_b32_e32 v11, 0xffff0000, v12
	v_pk_mul_f32 v[10:11], v[10:11], s[6:7] op_sel_hi:[1,0]
	v_mov_b32_e32 v16, v1
	v_cvt_pk_bf16_f32 v64, v10, v11
	v_lshlrev_b32_e32 v10, 16, v13
	v_and_b32_e32 v11, 0xffff0000, v13
	v_pk_mul_f32 v[10:11], v[10:11], s[6:7] op_sel_hi:[1,0]
	v_mov_b32_e32 v17, v1
	v_cvt_pk_bf16_f32 v65, v10, v11
	v_lshlrev_b32_e32 v10, 16, v6
	v_and_b32_e32 v11, 0xffff0000, v6
	v_lshlrev_b32_e32 v6, 16, v7
	v_and_b32_e32 v7, 0xffff0000, v7
	v_pk_mul_f32 v[6:7], v[6:7], s[6:7] op_sel_hi:[1,0]
	v_pk_mul_f32 v[10:11], v[10:11], s[6:7] op_sel_hi:[1,0]
	v_cvt_pk_bf16_f32 v67, v6, v7
	v_lshlrev_b32_e32 v6, 16, v8
	v_and_b32_e32 v7, 0xffff0000, v8
	v_pk_mul_f32 v[6:7], v[6:7], s[6:7] op_sel_hi:[1,0]
	v_cvt_pk_bf16_f32 v54, v22, v23
	v_cvt_pk_bf16_f32 v68, v6, v7
	v_lshlrev_b32_e32 v6, 16, v9
	v_and_b32_e32 v7, 0xffff0000, v9
	v_pk_mul_f32 v[6:7], v[6:7], s[6:7] op_sel_hi:[1,0]
	v_cvt_pk_bf16_f32 v62, v14, v15
	v_cvt_pk_bf16_f32 v69, v6, v7
	v_lshlrev_b32_e32 v6, 16, v2
	v_and_b32_e32 v7, 0xffff0000, v2
	v_lshlrev_b32_e32 v2, 16, v3
	v_and_b32_e32 v3, 0xffff0000, v3
	v_pk_mul_f32 v[2:3], v[2:3], s[6:7] op_sel_hi:[1,0]
	v_pk_mul_f32 v[6:7], v[6:7], s[6:7] op_sel_hi:[1,0]
	v_cvt_pk_bf16_f32 v71, v2, v3
	v_lshlrev_b32_e32 v2, 16, v4
	v_and_b32_e32 v3, 0xffff0000, v4
	v_pk_mul_f32 v[2:3], v[2:3], s[6:7] op_sel_hi:[1,0]
	v_mul_lo_u32 v4, v21, 24
	v_cvt_pk_bf16_f32 v72, v2, v3
	v_lshlrev_b32_e32 v2, 16, v5
	v_and_b32_e32 v3, 0xffff0000, v5
	v_pk_mul_f32 v[2:3], v[2:3], s[6:7] op_sel_hi:[1,0]
	v_cvt_pk_bf16_f32 v66, v10, v11
	v_cvt_pk_bf16_f32 v73, v2, v3
	v_mad_u64_u32 v[2:3], s[6:7], v21, s72, v[24:25]
	v_lshlrev_b32_e32 v88, 1, v2
	v_add_lshl_u32 v89, v2, v4, 1
	v_add_u32_e32 v3, 0, v88
	v_add_u32_e32 v2, 0, v89
	ds_write_b128 v3, v[50:53]
	ds_write_b128 v2, v[58:61] offset:9216
	v_lshl_add_u64 v[2:3], s[46:47], 0, v[26:27]
	v_lshl_add_u64 v[74:75], v[2:3], 0, s[0:1]
	v_lshl_add_u64 v[76:77], v[2:3], 0, s[4:5]
	v_lshrrev_b32_e32 v2, 2, v18
	v_and_or_b32 v2, v2, 3, v87
	v_lshlrev_b32_e32 v4, 2, v18
	v_and_b32_e32 v3, 16, v18
	v_and_b32_e32 v4, 12, v4
	v_mul_u32_u24_e32 v2, 0x60, v2
	v_or3_b32 v2, v4, v3, v2
	v_cvt_pk_bf16_f32 v70, v6, v7
	s_lshl_b32 s3, s3, 2
	v_cmp_gt_u32_e64 s[0:1], 32, v25
	v_cmp_eq_u32_e64 s[38:39], 0, v25
	v_mul_u32_u24_e32 v90, 0x90, v19
	v_lshlrev_b32_e32 v91, 1, v2
	s_lshl_b32 s2, s2, 8
	v_add_u32_e32 v95, s33, v21
	v_mov_b32_e32 v2, v1
	v_mov_b32_e32 v3, v1
	v_mov_b32_e32 v4, v1
	v_mov_b32_e32 v5, v1
	v_mov_b32_e32 v6, v1
	v_mov_b32_e32 v7, v1
	v_mov_b32_e32 v8, v1
	v_mov_b32_e32 v9, v1
	v_mov_b32_e32 v10, v1
	v_mov_b32_e32 v11, v1
	v_mov_b32_e32 v12, v1
	v_mov_b32_e32 v13, v1
	v_mov_b32_e32 v14, v1
	v_mov_b32_e32 v15, v1
	v_mov_b64_e32 v[32:33], v[16:17]
	s_add_i32 s62, s3, 0
	s_or_b32 s63, s58, 30
	s_mov_b32 s65, 0
	v_or_b32_e32 v92, 0x1800, v91
	v_add_u32_e32 v93, 0x2400, v91
	v_add_u32_e32 v94, 0xc00, v91
	s_sub_i32 s64, 0xfff, s2
	s_mov_b64 s[2:3], 0
	v_mov_b32_e32 v79, 0
	v_mov_b64_e32 v[30:31], v[14:15]
	v_mov_b64_e32 v[28:29], v[12:13]
	v_mov_b64_e32 v[26:27], v[10:11]
	v_mov_b64_e32 v[24:25], v[8:9]
	v_mov_b64_e32 v[22:23], v[6:7]
	v_mov_b64_e32 v[20:21], v[4:5]
	v_mov_b64_e32 v[18:19], v[2:3]
	s_waitcnt lgkmcnt(0)
	s_barrier
	s_cmp_lt_u32 s65, s59
	s_cselect_b64 s[50:51], -1, 0
	s_cmp_ge_u32 s65, s59
	s_cbranch_scc1 .LBB0_478

; __device__ __forceinline__ unsigned pk2(float lo, float hi) { f32x2 v = {lo, hi}; bf16x2_t b = __builtin_convertvector(v, bf16x2_t); return __builtin_bit_cast(unsigned, b); }
; __device__ __forceinline__ float bflo(unsigned u) { return __uint_as_float(u << 16); }
; __device__ __forceinline__ float bfhi(unsigned u) { return __uint_as_float(u & 0xffff0000u); }
; __device__ __forceinline__ float silu(float g) { return g * __builtin_amdgcn_rcpf(1.0f + __expf(-g)); }
; template <int MODE>
; __device__ __forceinline__ void attn_item(const AttnP& p, int b, int h, int qb, LAS unsigned char* lds) {
;     ...
;     float ss = 0.f;
; #pragma unroll
;     for (int d = 0; d < DV / 32; ++d)
; #pragma unroll
;         for (int i = 0; i < 16; ++i) {
;             float o = O[0][d][i] * inv0;
;             if (MODE == 0) o -= O[NC - 1][d][i] * inv1;
;             O[0][d][i] = o; ss += o * o;
;         }
;     ss += __shfl_xor(ss, 32);
;     float rn = 1.0f / sqrtf(ss * (1.0f / DV) + 1e-6f);
;     if (MODE == 0) rn *= p.oml;
;     int qrow_e = qrow; asm volatile("" : "+v"(qrow_e));
;     const size_t trow = (size_t)(tok0 + qrow_e);
; #pragma unroll
;     for (int d = 0; d < DV / 32; ++d)
; #pragma unroll
;         for (int g = 0; g < 4; ++g) {
;             const int dd = d * 32 + 8 * g + 4 * hh;
;             const u32x2 gr = *(const u32x2*)(P + trow * PP + gcol + dd);
;             const f32x4 og = *(const f32x4*)(p.out_gain + gaincol + dd);
;             const float o0 = O[0][d][4 * g] * rn * og[0] * silu(bflo(gr.x)), o1 = O[0][d][4 * g + 1] * rn * og[1] * silu(bfhi(gr.x));
;             const float o2 = O[0][d][4 * g + 2] * rn * og[2] * silu(bflo(gr.y)), o3 = O[0][d][4 * g + 3] * rn * og[3] * silu(bfhi(gr.y));
;             u32x2 wv; wv.x = pk2(o0, o1); wv.y = pk2(o2, o3);
;             *(u32x2*)(p.mixed + trow * 1024 + mixcol + dd) = wv;
.Lnx_bs:
	v_mul_f32_e32 v0, v19, v19
	v_fmac_f32_e32 v0, v18, v18
	v_fmac_f32_e32 v0, v20, v20
	v_fmac_f32_e32 v0, v21, v21
	v_fmac_f32_e32 v0, v22, v22
	v_fmac_f32_e32 v0, v23, v23
	v_fmac_f32_e32 v0, v24, v24
	v_fmac_f32_e32 v0, v25, v25
	v_fmac_f32_e32 v0, v26, v26
	v_fmac_f32_e32 v0, v27, v27
	v_fmac_f32_e32 v0, v28, v28
	v_fmac_f32_e32 v0, v29, v29
	v_fmac_f32_e32 v0, v30, v30
	v_fmac_f32_e32 v0, v31, v31
	v_fmac_f32_e32 v0, v32, v32
	v_fmac_f32_e32 v0, v33, v33
	v_fmac_f32_e32 v0, v2, v2
	v_fmac_f32_e32 v0, v3, v3
	v_fmac_f32_e32 v0, v4, v4
	v_fmac_f32_e32 v0, v5, v5
	v_fmac_f32_e32 v0, v6, v6
	v_fmac_f32_e32 v0, v7, v7
	v_fmac_f32_e32 v0, v8, v8
	v_fmac_f32_e32 v0, v9, v9
	v_fmac_f32_e32 v0, v10, v10
	v_fmac_f32_e32 v0, v11, v11
	v_pk_mul_f32 v[38:39], v[12:13], v[12:13]
	v_pk_mul_f32 v[36:37], v[14:15], v[14:15]
	v_add_f32_e32 v0, v38, v0
	v_add_f32_e32 v0, v39, v0
	v_add_f32_e32 v0, v36, v0
	v_pk_mul_f32 v[34:35], v[16:17], v[16:17]
	v_add_f32_e32 v0, v37, v0
	v_add_f32_e32 v0, v34, v0
	v_add_f32_e32 v0, v35, v0
	ds_bpermute_b32 v34, v226, v0
	v_lshlrev_b32_e32 v39, 2, v87
	s_waitcnt lgkmcnt(0)
	v_add_f32_e32 v0, v0, v34
	v_fmamk_f32 v0, v0, 0x3c800000, v211
	v_cmp_gt_f32_e32 vcc, s74, v0
	v_mul_f32_e32 v34, 0x4f800000, v0
	s_nop 0
	v_cndmask_b32_e32 v0, v0, v34, vcc
	v_sqrt_f32_e32 v34, v0
	s_nop 0
	v_add_u32_e32 v35, -1, v34
	v_fma_f32 v36, -v35, v34, v0
	v_cmp_ge_f32_e64 s[0:1], 0, v36
	v_add_u32_e32 v36, 1, v34
	s_nop 0
	v_cndmask_b32_e64 v35, v34, v35, s[0:1]
	v_fma_f32 v34, -v36, v34, v0
	v_cmp_lt_f32_e64 s[0:1], 0, v34
	s_nop 1
	v_cndmask_b32_e64 v34, v35, v36, s[0:1]
	v_mul_f32_e32 v35, 0x37800000, v34
	v_cndmask_b32_e32 v34, v34, v35, vcc
	v_cmp_class_f32_e32 vcc, v0, v212
	s_nop 1
	v_cndmask_b32_e32 v0, v34, v0, vcc
	v_div_scale_f32 v34, s[0:1], v0, v0, 1.0
	v_rcp_f32_e32 v35, v34
	s_nop 0
	v_fma_f32 v36, -v34, v35, 1.0
	v_fmac_f32_e32 v35, v36, v35
	v_div_scale_f32 v36, vcc, 1.0, v0, 1.0
	v_mul_f32_e32 v37, v36, v35
	v_fma_f32 v38, -v34, v37, v36
	v_fmac_f32_e32 v37, v38, v35
	v_fma_f32 v34, -v34, v37, v36
	v_div_fmas_f32 v34, v34, v35, v37
	v_div_fixup_f32 v38, v34, v0, 1.0
	v_add_u32_e32 v34, s33, v86
	v_mov_b64_e32 v[36:37], s[46:47]
	v_mad_i64_i32 v[36:37], s[0:1], v34, s76, v[36:37]
	v_lshl_add_u64 v[36:37], v[36:37], 0, s[92:93]
	s_mov_b64 s[0:1], 0x1c00
	v_ashrrev_i32_e32 v35, 31, v34
	v_lshl_add_u64 v[40:41], v[36:37], 0, s[0:1]
	v_lshlrev_b32_e32 v0, 1, v87
	s_lshl_b32 s0, s20, 2
	v_lshlrev_b64 v[42:43], 11, v[34:35]
	v_lshl_add_u64 v[34:35], v[40:41], 0, v[0:1]
	s_add_u32 s0, s54, s0
	v_mov_b64_e32 v[44:45], v[166:167]
	v_mov_b64_e32 v[122:123], v[168:169]
	v_mov_b64_e32 v[124:125], v[170:171]
	v_mov_b64_e32 v[126:127], v[172:173]
	v_mov_b64_e32 v[128:129], v[174:175]
	v_mov_b64_e32 v[130:131], v[176:177]
	v_mov_b64_e32 v[132:133], v[178:179]
	v_mov_b64_e32 v[134:135], v[180:181]
	s_addc_u32 s1, s55, 0
	global_load_dwordx4 v[34:37], v39, s[0:1] offset:2048
	global_load_dwordx4 v[136:139], v39, s[0:1] offset:2080
	global_load_dwordx4 v[140:143], v39, s[0:1] offset:2112
	global_load_dwordx4 v[144:147], v39, s[0:1] offset:2144
	global_load_dwordx4 v[148:151], v39, s[0:1] offset:2176
	global_load_dwordx4 v[152:155], v39, s[0:1] offset:2208
	global_load_dwordx4 v[156:159], v39, s[0:1] offset:2240
	global_load_dwordx4 v[160:163], v39, s[0:1] offset:2272
	v_pk_mul_f32 v[18:19], v[18:19], v[38:39] op_sel_hi:[1,0]
	v_pk_mul_f32 v[20:21], v[20:21], v[38:39] op_sel_hi:[1,0]
	v_pk_mul_f32 v[22:23], v[22:23], v[38:39] op_sel_hi:[1,0]
	v_pk_mul_f32 v[24:25], v[24:25], v[38:39] op_sel_hi:[1,0]
	v_pk_mul_f32 v[26:27], v[26:27], v[38:39] op_sel_hi:[1,0]
	v_pk_mul_f32 v[28:29], v[28:29], v[38:39] op_sel_hi:[1,0]
	v_pk_mul_f32 v[30:31], v[30:31], v[38:39] op_sel_hi:[1,0]
	v_pk_mul_f32 v[2:3], v[2:3], v[38:39] op_sel_hi:[1,0]
	v_pk_mul_f32 v[4:5], v[4:5], v[38:39] op_sel_hi:[1,0]
	v_pk_mul_f32 v[6:7], v[6:7], v[38:39] op_sel_hi:[1,0]
	v_pk_mul_f32 v[8:9], v[8:9], v[38:39] op_sel_hi:[1,0]
	v_pk_mul_f32 v[10:11], v[10:11], v[38:39] op_sel_hi:[1,0]
	s_waitcnt vmcnt(0) lgkmcnt(0)
	v_lshlrev_b32_e32 v46, 16, v44
	v_and_b32_e32 v47, 0xffff0000, v44
	v_mul_f32_e32 v44, 0xbfb8aa3b, v46
	v_pk_mul_f32 v[18:19], v[34:35], v[18:19]
	v_mul_f32_e32 v34, 0xbfb8aa3b, v47
	v_exp_f32_e32 v44, v44
	v_exp_f32_e32 v34, v34
	v_pk_mul_f32 v[20:21], v[36:37], v[20:21]
	v_add_f32_e32 v44, 1.0, v44
	v_add_f32_e32 v34, 1.0, v34
	v_rcp_f32_e32 v48, v44
	v_rcp_f32_e32 v49, v34
	s_nop 0
	v_pk_mul_f32 v[34:35], v[48:49], v[46:47]
	s_nop 0
	v_pk_mul_f32 v[18:19], v[18:19], v[34:35]
	v_lshlrev_b32_e32 v34, 16, v45
	v_and_b32_e32 v35, 0xffff0000, v45
	v_mul_f32_e32 v44, 0xbfb8aa3b, v34
	v_mul_f32_e32 v36, 0xbfb8aa3b, v35
	v_exp_f32_e32 v44, v44
	v_exp_f32_e32 v36, v36
	v_add_f32_e32 v44, 1.0, v44
	v_add_f32_e32 v36, 1.0, v36
	v_rcp_f32_e32 v44, v44
	v_rcp_f32_e32 v45, v36
	s_nop 0
	v_pk_mul_f32 v[34:35], v[44:45], v[34:35]
	s_nop 0
	v_pk_mul_f32 v[20:21], v[20:21], v[34:35]
	v_cvt_pk_bf16_f32 v34, v18, v19
	v_lshl_add_u64 v[18:19], s[44:45], 0, v[42:43]
	v_lshl_add_u64 v[18:19], v[18:19], 0, s[92:93]
	v_cvt_pk_bf16_f32 v35, v20, v21
	v_lshl_add_u64 v[18:19], v[18:19], 0, v[0:1]
	v_or_b32_e32 v20, 16, v0
	v_mov_b32_e32 v21, v1
	global_store_dwordx2 v[18:19], v[34:35], off offset:1024
	v_lshl_add_u64 v[20:21], v[40:41], 0, v[20:21]
	v_mov_b64_e32 v[20:21], v[122:123]
	s_nop 0
	v_mov_b64_e32 v[34:35], v[136:137]
	v_mov_b64_e32 v[36:37], v[138:139]
	v_lshlrev_b32_e32 v42, 16, v20
	v_and_b32_e32 v43, 0xffff0000, v20
	v_mul_f32_e32 v20, 0xbfb8aa3b, v42
	v_exp_f32_e32 v20, v20
	v_pk_mul_f32 v[22:23], v[34:35], v[22:23]
	v_pk_mul_f32 v[24:25], v[36:37], v[24:25]
; __device__ __forceinline__ unsigned pk2(float lo, float hi) { f32x2 v = {lo, hi}; bf16x2_t b = __builtin_convertvector(v, bf16x2_t); return __builtin_bit_cast(unsigned, b); }
; __device__ __forceinline__ float bflo(unsigned u) { return __uint_as_float(u << 16); }
; __device__ __forceinline__ float bfhi(unsigned u) { return __uint_as_float(u & 0xffff0000u); }
; __device__ __forceinline__ float silu(float g) { return g * __builtin_amdgcn_rcpf(1.0f + __expf(-g)); }
; template <int MODE>
; __device__ __forceinline__ void attn_item(const AttnP& p, int b, int h, int qb, LAS unsigned char* lds) {
;     ...
;         for (int g = 0; g < 4; ++g) {
;             const int dd = d * 32 + 8 * g + 4 * hh;
;             const u32x2 gr = *(const u32x2*)(P + trow * PP + gcol + dd);
;             const f32x4 og = *(const f32x4*)(p.out_gain + gaincol + dd);
;             const float o0 = O[0][d][4 * g] * rn * og[0] * silu(bflo(gr.x)), o1 = O[0][d][4 * g + 1] * rn * og[1] * silu(bfhi(gr.x));
;             const float o2 = O[0][d][4 * g + 2] * rn * og[2] * silu(bflo(gr.y)), o3 = O[0][d][4 * g + 3] * rn * og[3] * silu(bfhi(gr.y));
;             u32x2 wv; wv.x = pk2(o0, o1); wv.y = pk2(o2, o3);
;             *(u32x2*)(p.mixed + trow * 1024 + mixcol + dd) = wv;
	v_add_f32_e32 v20, 1.0, v20
	v_rcp_f32_e32 v44, v20
	v_mul_f32_e32 v20, 0xbfb8aa3b, v43
	v_exp_f32_e32 v20, v20
	s_nop 0
	v_add_f32_e32 v20, 1.0, v20
	v_rcp_f32_e32 v45, v20
	v_lshlrev_b32_e32 v20, 16, v21
	v_and_b32_e32 v21, 0xffff0000, v21
	v_pk_mul_f32 v[34:35], v[44:45], v[42:43]
	s_nop 0
	v_pk_mul_f32 v[22:23], v[22:23], v[34:35]
	v_mul_f32_e32 v34, 0xbfb8aa3b, v20
	v_mul_f32_e32 v35, 0xbfb8aa3b, v21
	v_exp_f32_e32 v34, v34
	v_exp_f32_e32 v35, v35
	v_cvt_pk_bf16_f32 v22, v22, v23
	v_add_f32_e32 v34, 1.0, v34
	v_add_f32_e32 v35, 1.0, v35
	v_rcp_f32_e32 v34, v34
	v_rcp_f32_e32 v35, v35
	s_nop 0
	v_pk_mul_f32 v[20:21], v[34:35], v[20:21]
	s_nop 0
	v_pk_mul_f32 v[20:21], v[24:25], v[20:21]
	s_nop 0
	v_cvt_pk_bf16_f32 v23, v20, v21
	v_or_b32_e32 v20, 32, v0
	v_mov_b32_e32 v21, v1
	global_store_dwordx2 v[18:19], v[22:23], off offset:1040
	v_lshl_add_u64 v[20:21], v[40:41], 0, v[20:21]
	v_mov_b64_e32 v[24:25], v[124:125]
	s_nop 0
	v_mov_b64_e32 v[20:21], v[140:141]
	v_mov_b64_e32 v[22:23], v[142:143]
	v_lshlrev_b32_e32 v34, 16, v24
	v_and_b32_e32 v35, 0xffff0000, v24
	v_mul_f32_e32 v24, 0xbfb8aa3b, v34
	v_exp_f32_e32 v24, v24
	v_pk_mul_f32 v[20:21], v[26:27], v[20:21]
	v_pk_mul_f32 v[22:23], v[28:29], v[22:23]
	v_add_f32_e32 v24, 1.0, v24
	v_rcp_f32_e32 v36, v24
	v_mul_f32_e32 v24, 0xbfb8aa3b, v35
	v_exp_f32_e32 v24, v24
	s_nop 0
	v_add_f32_e32 v24, 1.0, v24
	v_rcp_f32_e32 v37, v24
	v_lshlrev_b32_e32 v24, 16, v25
	v_and_b32_e32 v25, 0xffff0000, v25
	v_pk_mul_f32 v[26:27], v[36:37], v[34:35]
	s_nop 0
	v_pk_mul_f32 v[20:21], v[20:21], v[26:27]
	v_mul_f32_e32 v26, 0xbfb8aa3b, v24
	v_mul_f32_e32 v27, 0xbfb8aa3b, v25
	v_exp_f32_e32 v26, v26
	v_exp_f32_e32 v27, v27
	v_cvt_pk_bf16_f32 v20, v20, v21
	v_add_f32_e32 v26, 1.0, v26
	v_add_f32_e32 v27, 1.0, v27
	v_rcp_f32_e32 v26, v26
	v_rcp_f32_e32 v27, v27
	s_nop 0
	v_pk_mul_f32 v[24:25], v[26:27], v[24:25]
	s_nop 0
	v_pk_mul_f32 v[22:23], v[22:23], v[24:25]
	s_nop 0
	v_cvt_pk_bf16_f32 v21, v22, v23
	global_store_dwordx2 v[18:19], v[20:21], off offset:1056
	v_or_b32_e32 v20, 48, v0
	v_mov_b32_e32 v21, v1
	v_lshl_add_u64 v[20:21], v[40:41], 0, v[20:21]
	v_mov_b64_e32 v[24:25], v[126:127]
	s_nop 0
	v_mov_b64_e32 v[20:21], v[144:145]
	v_mov_b64_e32 v[22:23], v[146:147]
	v_lshlrev_b32_e32 v26, 16, v24
	v_and_b32_e32 v27, 0xffff0000, v24
	v_mul_f32_e32 v24, 0xbfb8aa3b, v26
	v_exp_f32_e32 v24, v24
	v_pk_mul_f32 v[20:21], v[30:31], v[20:21]
	v_add_f32_e32 v24, 1.0, v24
	v_rcp_f32_e32 v28, v24
	v_mul_f32_e32 v24, 0xbfb8aa3b, v27
	v_exp_f32_e32 v24, v24
	s_nop 0
	v_add_f32_e32 v24, 1.0, v24
	v_rcp_f32_e32 v29, v24
	v_lshlrev_b32_e32 v24, 16, v25
	v_and_b32_e32 v25, 0xffff0000, v25
	v_pk_mul_f32 v[26:27], v[28:29], v[26:27]
	s_nop 0
	v_pk_mul_f32 v[20:21], v[20:21], v[26:27]
	v_mul_f32_e32 v26, 0xbfb8aa3b, v24
	v_mul_f32_e32 v27, 0xbfb8aa3b, v25
	v_exp_f32_e32 v26, v26
	v_exp_f32_e32 v27, v27
	v_pk_mul_f32 v[28:29], v[32:33], v[38:39] op_sel_hi:[1,0]
	v_cvt_pk_bf16_f32 v20, v20, v21
	v_add_f32_e32 v26, 1.0, v26
	v_add_f32_e32 v27, 1.0, v27
	v_rcp_f32_e32 v26, v26
	v_rcp_f32_e32 v27, v27
	v_pk_mul_f32 v[22:23], v[28:29], v[22:23]
	v_pk_mul_f32 v[24:25], v[26:27], v[24:25]
	s_nop 0
	v_pk_mul_f32 v[22:23], v[22:23], v[24:25]
	s_nop 0
	v_cvt_pk_bf16_f32 v21, v22, v23
	global_store_dwordx2 v[18:19], v[20:21], off offset:1072
	v_or_b32_e32 v20, 64, v0
	v_mov_b32_e32 v21, v1
	v_lshl_add_u64 v[20:21], v[40:41], 0, v[20:21]
	v_mov_b64_e32 v[20:21], v[128:129]
	s_nop 0
	v_mov_b64_e32 v[22:23], v[148:149]
	v_mov_b64_e32 v[24:25], v[150:151]
	v_lshlrev_b32_e32 v26, 16, v20
	v_and_b32_e32 v27, 0xffff0000, v20
	v_mul_f32_e32 v20, 0xbfb8aa3b, v26
	v_exp_f32_e32 v20, v20
	v_pk_mul_f32 v[2:3], v[2:3], v[22:23]
	v_pk_mul_f32 v[4:5], v[4:5], v[24:25]
	v_add_f32_e32 v20, 1.0, v20
	v_rcp_f32_e32 v28, v20
	v_mul_f32_e32 v20, 0xbfb8aa3b, v27
	v_exp_f32_e32 v20, v20
	s_nop 0
	v_add_f32_e32 v20, 1.0, v20
	v_rcp_f32_e32 v29, v20
	v_lshlrev_b32_e32 v20, 16, v21
	v_and_b32_e32 v21, 0xffff0000, v21
	v_pk_mul_f32 v[22:23], v[28:29], v[26:27]
	s_nop 0
	v_pk_mul_f32 v[2:3], v[2:3], v[22:23]
; __device__ __forceinline__ unsigned pk2(float lo, float hi) { f32x2 v = {lo, hi}; bf16x2_t b = __builtin_convertvector(v, bf16x2_t); return __builtin_bit_cast(unsigned, b); }
; __device__ __forceinline__ float bflo(unsigned u) { return __uint_as_float(u << 16); }
; __device__ __forceinline__ float bfhi(unsigned u) { return __uint_as_float(u & 0xffff0000u); }
; __device__ __forceinline__ float silu(float g) { return g * __builtin_amdgcn_rcpf(1.0f + __expf(-g)); }
; template <int MODE>
; __device__ __forceinline__ void attn_item(const AttnP& p, int b, int h, int qb, LAS unsigned char* lds) {
;     ...
;         for (int g = 0; g < 4; ++g) {
;             const int dd = d * 32 + 8 * g + 4 * hh;
;             const u32x2 gr = *(const u32x2*)(P + trow * PP + gcol + dd);
;             const f32x4 og = *(const f32x4*)(p.out_gain + gaincol + dd);
;             const float o0 = O[0][d][4 * g] * rn * og[0] * silu(bflo(gr.x)), o1 = O[0][d][4 * g + 1] * rn * og[1] * silu(bfhi(gr.x));
;             const float o2 = O[0][d][4 * g + 2] * rn * og[2] * silu(bflo(gr.y)), o3 = O[0][d][4 * g + 3] * rn * og[3] * silu(bfhi(gr.y));
;             u32x2 wv; wv.x = pk2(o0, o1); wv.y = pk2(o2, o3);
;             *(u32x2*)(p.mixed + trow * 1024 + mixcol + dd) = wv;
	v_mul_f32_e32 v22, 0xbfb8aa3b, v20
	v_mul_f32_e32 v23, 0xbfb8aa3b, v21
	v_exp_f32_e32 v22, v22
	v_exp_f32_e32 v23, v23
	v_cvt_pk_bf16_f32 v2, v2, v3
	v_add_f32_e32 v22, 1.0, v22
	v_add_f32_e32 v23, 1.0, v23
	v_rcp_f32_e32 v22, v22
	v_rcp_f32_e32 v23, v23
	s_nop 0
	v_pk_mul_f32 v[20:21], v[22:23], v[20:21]
	s_nop 0
	v_pk_mul_f32 v[4:5], v[4:5], v[20:21]
	s_nop 0
	v_cvt_pk_bf16_f32 v3, v4, v5
	global_store_dwordx2 v[18:19], v[2:3], off offset:1088
	v_or_b32_e32 v2, 0x50, v0
	v_mov_b32_e32 v3, v1
	v_lshl_add_u64 v[2:3], v[40:41], 0, v[2:3]
	v_mov_b64_e32 v[20:21], v[130:131]
	s_nop 0
	v_mov_b64_e32 v[2:3], v[152:153]
	v_mov_b64_e32 v[4:5], v[154:155]
	v_lshlrev_b32_e32 v22, 16, v20
	v_and_b32_e32 v23, 0xffff0000, v20
	v_mul_f32_e32 v20, 0xbfb8aa3b, v22
	v_pk_mul_f32 v[2:3], v[6:7], v[2:3]
	v_mul_f32_e32 v6, 0xbfb8aa3b, v23
	v_exp_f32_e32 v20, v20
	v_exp_f32_e32 v6, v6
	v_pk_mul_f32 v[4:5], v[8:9], v[4:5]
	v_add_f32_e32 v20, 1.0, v20
	v_add_f32_e32 v6, 1.0, v6
	v_rcp_f32_e32 v24, v20
	v_rcp_f32_e32 v25, v6
	s_nop 0
	v_pk_mul_f32 v[6:7], v[24:25], v[22:23]
	s_nop 0
	v_pk_mul_f32 v[2:3], v[2:3], v[6:7]
	v_lshlrev_b32_e32 v6, 16, v21
	v_and_b32_e32 v7, 0xffff0000, v21
	v_mul_f32_e32 v20, 0xbfb8aa3b, v6
	v_mul_f32_e32 v8, 0xbfb8aa3b, v7
	v_exp_f32_e32 v20, v20
	v_exp_f32_e32 v8, v8
	v_cvt_pk_bf16_f32 v2, v2, v3
	v_add_f32_e32 v20, 1.0, v20
	v_add_f32_e32 v8, 1.0, v8
	v_rcp_f32_e32 v20, v20
	v_rcp_f32_e32 v21, v8
	s_nop 0
	v_pk_mul_f32 v[6:7], v[20:21], v[6:7]
	s_nop 0
	v_pk_mul_f32 v[4:5], v[4:5], v[6:7]
	s_nop 0
	v_cvt_pk_bf16_f32 v3, v4, v5
	global_store_dwordx2 v[18:19], v[2:3], off offset:1104
	v_or_b32_e32 v2, 0x60, v0
	v_mov_b32_e32 v3, v1
	v_lshl_add_u64 v[2:3], v[40:41], 0, v[2:3]
	v_mov_b64_e32 v[6:7], v[132:133]
	s_nop 0
	v_mov_b64_e32 v[2:3], v[156:157]
	v_mov_b64_e32 v[4:5], v[158:159]
	v_or_b32_e32 v0, 0x70, v0
	v_lshlrev_b32_e32 v8, 16, v6
	v_and_b32_e32 v9, 0xffff0000, v6
	v_mul_f32_e32 v6, 0xbfb8aa3b, v8
	v_exp_f32_e32 v6, v6
	v_pk_mul_f32 v[2:3], v[10:11], v[2:3]
	v_pk_mul_f32 v[10:11], v[12:13], v[38:39] op_sel_hi:[1,0]
	v_pk_mul_f32 v[12:13], v[14:15], v[38:39] op_sel_hi:[1,0]
	v_add_f32_e32 v6, 1.0, v6
	v_rcp_f32_e32 v20, v6
	v_mul_f32_e32 v6, 0xbfb8aa3b, v9
	v_exp_f32_e32 v6, v6
	v_pk_mul_f32 v[4:5], v[10:11], v[4:5]
	v_add_f32_e32 v6, 1.0, v6
	v_rcp_f32_e32 v21, v6
	v_lshlrev_b32_e32 v6, 16, v7
	v_and_b32_e32 v7, 0xffff0000, v7
	v_pk_mul_f32 v[8:9], v[20:21], v[8:9]
	s_nop 0
	v_pk_mul_f32 v[2:3], v[2:3], v[8:9]
	v_mul_f32_e32 v8, 0xbfb8aa3b, v6
	v_mul_f32_e32 v9, 0xbfb8aa3b, v7
	v_exp_f32_e32 v8, v8
	v_exp_f32_e32 v9, v9
	v_cvt_pk_bf16_f32 v2, v2, v3
	v_add_f32_e32 v8, 1.0, v8
	v_add_f32_e32 v9, 1.0, v9
	v_rcp_f32_e32 v8, v8
	v_rcp_f32_e32 v9, v9
	s_nop 0
	v_pk_mul_f32 v[6:7], v[8:9], v[6:7]
	s_nop 0
	v_pk_mul_f32 v[4:5], v[4:5], v[6:7]
	s_nop 0
	v_cvt_pk_bf16_f32 v3, v4, v5
	global_store_dwordx2 v[18:19], v[2:3], off offset:1120
	v_lshl_add_u64 v[2:3], v[40:41], 0, v[0:1]
	v_mov_b64_e32 v[2:3], v[134:135]
	s_nop 0
	v_mov_b64_e32 v[4:5], v[160:161]
	v_mov_b64_e32 v[6:7], v[162:163]
	s_mov_b64 s[0:1], 0
	v_lshlrev_b32_e32 v8, 16, v2
	v_mul_f32_e32 v0, 0xbfb8aa3b, v8
	v_exp_f32_e32 v0, v0
	v_and_b32_e32 v9, 0xffff0000, v2
	v_lshlrev_b32_e32 v2, 16, v3
	v_pk_mul_f32 v[4:5], v[12:13], v[4:5]
	v_add_f32_e32 v0, 1.0, v0
	v_rcp_f32_e32 v10, v0
	v_mul_f32_e32 v0, 0xbfb8aa3b, v9
	v_exp_f32_e32 v0, v0
	v_and_b32_e32 v3, 0xffff0000, v3
	v_add_f32_e32 v0, 1.0, v0
	v_rcp_f32_e32 v11, v0
	v_mul_f32_e32 v0, 0xbfb8aa3b, v2
	v_exp_f32_e32 v0, v0
	v_pk_mul_f32 v[8:9], v[10:11], v[8:9]
	s_nop 0
	v_pk_mul_f32 v[4:5], v[4:5], v[8:9]
	v_add_f32_e32 v0, 1.0, v0
	v_rcp_f32_e32 v8, v0
	v_mul_f32_e32 v0, 0xbfb8aa3b, v3
	v_exp_f32_e32 v0, v0
	v_pk_mul_f32 v[10:11], v[16:17], v[38:39] op_sel_hi:[1,0]
	v_cvt_pk_bf16_f32 v4, v4, v5
	v_pk_mul_f32 v[6:7], v[10:11], v[6:7]
	v_add_f32_e32 v0, 1.0, v0
	v_rcp_f32_e32 v9, v0
	s_nop 0
	v_pk_mul_f32 v[2:3], v[8:9], v[2:3]
	s_nop 0
	v_pk_mul_f32 v[2:3], v[6:7], v[2:3]
	s_nop 0
	v_cvt_pk_bf16_f32 v5, v2, v3
	global_store_dwordx2 v[18:19], v[4:5], off offset:1136
